# sample attention loop: K fragments prefetched at iteration top + two 4-wave halves staggered by one barrier (extra mid-loop barrier) so one half's QK MFMAs run beside the other's softmax VALU
# speedup vs baseline: 1.0108x; 1.0108x over previous
.LBB0_374:
	s_andn2_saveexec_b64 s[0:1], s[0:1]
	v_lshlrev_b64 v[0:1], 10, v[2:3]
	v_lshl_add_u64 v[0:1], s[2:3], 0, v[0:1]
	v_mov_b32_e32 v13, v137
	v_lshl_add_u64 v[0:1], v[0:1], 0, v[12:13]
	s_or_b64 exec, exec, s[0:1]
	s_ashr_i32 s71, s70, 31
	s_lshl_b64 s[0:1], s[70:71], 1
	v_readlane_b32 s4, v252, 63
	v_readlane_b32 s5, v253, 0
	s_add_u32 s0, s4, s0
	s_addc_u32 s1, s5, s1
	v_mov_b32_e32 v15, v137
	global_load_dwordx4 v[104:107], v[0:1], off
	v_lshl_add_u64 v[0:1], s[0:1], 0, v[14:15]
	v_lshl_add_u64 v[2:3], v[0:1], 0, v[136:137]
	v_mov_b32_e32 v121, v137
	v_lshl_add_u64 v[0:1], v[0:1], 0, v[120:121]
	global_load_dwordx4 v[108:111], v[2:3], off
	global_load_dwordx4 v[112:115], v[0:1], off
	v_lshl_add_u64 v[122:123], s[4:5], 0, v[14:15]
	v_readlane_b32 s4, v253, 3
	s_add_i32 s0, s22, 0x2080
	v_mov_b32_e32 v9, v137
	v_readlane_b32 s5, v253, 4
	v_mov_b32_e32 v11, v137
	v_mov_b32_e32 v13, v137
	v_mov_b32_e32 v14, v137
	v_lshlrev_b32_e32 v118, 3, v19
	v_mul_u32_u24_e32 v152, 0x90, v16
	v_mul_u32_u24_e32 v153, 0x90, v17
	v_lshl_add_u32 v154, v19, 4, s24
	v_lshl_add_u64 v[124:125], s[4:5], 0, v[8:9]
	v_lshl_add_u64 v[126:127], s[2:3], 0, v[8:9]
	v_lshl_add_u64 v[128:129], s[4:5], 0, v[10:11]
	v_lshl_add_u64 v[130:131], s[2:3], 0, v[10:11]
	v_lshl_add_u64 v[132:133], s[4:5], 0, v[12:13]
	v_lshl_add_u64 v[134:135], s[2:3], 0, v[12:13]
	v_mul_u32_u24_e32 v155, 0xd0, v18
	v_mul_u32_u24_e32 v142, 0x90, v18
	v_add_u32_sdwa v156, s0, v22 dst_sel:DWORD dst_unused:UNUSED_PAD src0_sel:DWORD src1_sel:WORD_1
	v_add_u32_sdwa v157, s0, v21 dst_sel:DWORD dst_unused:UNUSED_PAD src0_sel:DWORD src1_sel:WORD_1
	v_add_u32_e32 v158, s0, v20
	v_mov_b32_e32 v0, v137
	v_mov_b32_e32 v1, v137
	v_mov_b32_e32 v2, v137
	v_mov_b32_e32 v3, v137
	v_mov_b32_e32 v4, v137
	v_mov_b32_e32 v5, v137
	v_mov_b32_e32 v6, v137
	v_mov_b32_e32 v7, v137
	v_mov_b32_e32 v8, v137
	v_mov_b32_e32 v10, v137
	v_mov_b32_e32 v12, v137
	v_mov_b64_e32 v[30:31], v[14:15]
	v_add_u32_e32 v143, s24, v118
	s_mov_b32 s1, 0
	v_mov_b32_e32 v151, 0xf149f2ca
	v_mov_b32_e32 v119, 0
	v_mov_b64_e32 v[28:29], v[12:13]
	v_mov_b64_e32 v[26:27], v[10:11]
	v_mov_b64_e32 v[24:25], v[8:9]
	v_mov_b64_e32 v[22:23], v[6:7]
	v_mov_b64_e32 v[20:21], v[4:5]
	v_mov_b64_e32 v[18:19], v[2:3]
	v_mov_b64_e32 v[16:17], v[0:1]
	s_mov_b32 s3, 0
	s_waitcnt lgkmcnt(0)
	s_barrier
	v_readfirstlane_b32 s22, v139
	s_bitcmp1_b32 s22, 8
	s_cbranch_scc0 .Lsa_no_e1
	s_barrier
.Lsa_no_e1:
.LBB0_377:
	s_and_b32 s22, s3, 1
	s_mul_i32 s22, s22, 0x3400
	v_add3_u32 v238, v154, s22, v155
	ds_read_b128 v[190:193], v238
	ds_read_b128 v[194:197], v238 offset:32
	ds_read_b128 v[198:201], v238 offset:64
	ds_read_b128 v[202:205], v238 offset:96
	ds_read_b128 v[206:209], v238 offset:128
	ds_read_b128 v[210:213], v238 offset:160
	ds_read_b128 v[214:217], v238 offset:6656
	ds_read_b128 v[218:221], v238 offset:6688
	ds_read_b128 v[222:225], v238 offset:6720
	ds_read_b128 v[226:229], v238 offset:6752
	ds_read_b128 v[230:233], v238 offset:6784
	ds_read_b128 v[234:237], v238 offset:6816
	s_add_i32 s2, s3, 1
	s_bitcmp1_b32 s2, 0
	s_cselect_b32 s22, 0x3400, 0
	s_cselect_b32 s23, 0x2400, 0
	s_add_i32 s22, s24, s22
	v_add3_u32 v32, s22, v144, v145
	s_waitcnt vmcnt(4)
	ds_write_b128 v32, v[96:99]
	v_add3_u32 v32, s22, v146, v147
	s_waitcnt vmcnt(3)
	ds_write_b128 v32, v[100:103]
	v_add3_u32 v32, s22, v148, v149
	s_waitcnt vmcnt(2)
	ds_write_b128 v32, v[104:107]
	v_add_u32_e32 v32, s23, v150
	v_add_u32_e32 v33, v32, v152
	v_add_u32_e32 v32, v32, v153
	s_cmpk_gt_u32 s3, 0x45
	s_waitcnt vmcnt(1)
	ds_write_b128 v33, v[108:111] offset:26624
	s_waitcnt vmcnt(0)
	ds_write_b128 v32, v[112:115] offset:26624
	s_cbranch_scc1 .LBB0_379
	v_add_u32_e32 v32, s1, v158
	v_ashrrev_i32_e32 v33, 31, v32
	v_lshlrev_b64 v[34:35], 10, v[32:33]
	v_lshlrev_b64 v[32:33], 6, v[32:33]
	s_movk_i32 s4, 0xff80
	v_lshl_add_u64 v[32:33], v[124:125], 0, v[32:33]
	s_mov_b32 s5, -1
	v_lshl_add_u64 v[34:35], v[126:127], 0, v[34:35]
	v_lshl_add_u64 v[32:33], v[32:33], 0, s[4:5]
	v_cndmask_b32_e64 v33, v33, v35, s[40:41]
	v_cndmask_b32_e64 v32, v32, v34, s[40:41]
	global_load_dwordx4 v[96:99], v[32:33], off
	v_add_u32_e32 v32, s1, v157
	v_ashrrev_i32_e32 v33, 31, v32
	v_lshlrev_b64 v[34:35], 10, v[32:33]
	v_lshlrev_b64 v[32:33], 6, v[32:33]
	v_lshl_add_u64 v[32:33], v[128:129], 0, v[32:33]
	v_lshl_add_u64 v[34:35], v[130:131], 0, v[34:35]
	v_lshl_add_u64 v[32:33], v[32:33], 0, s[4:5]
	v_cndmask_b32_e64 v33, v33, v35, s[42:43]
	v_cndmask_b32_e64 v32, v32, v34, s[42:43]
	global_load_dwordx4 v[100:103], v[32:33], off
	v_add_u32_e32 v32, s1, v156
	v_ashrrev_i32_e32 v33, 31, v32
	v_lshlrev_b64 v[34:35], 10, v[32:33]
	v_lshlrev_b64 v[32:33], 6, v[32:33]
	v_lshl_add_u64 v[32:33], v[132:133], 0, v[32:33]
	s_add_i32 s22, s0, s1
	v_lshl_add_u64 v[34:35], v[134:135], 0, v[34:35]
	v_lshl_add_u64 v[32:33], v[32:33], 0, s[4:5]
	v_cndmask_b32_e64 v33, v33, v35, s[44:45]
	v_cndmask_b32_e64 v32, v32, v34, s[44:45]
	s_ashr_i32 s23, s22, 31
	global_load_dwordx4 v[104:107], v[32:33], off
	v_lshl_add_u64 v[32:33], s[22:23], 1, v[122:123]
	v_lshl_add_u64 v[34:35], v[32:33], 0, v[136:137]
	v_mov_b32_e32 v121, v137
	v_lshl_add_u64 v[32:33], v[32:33], 0, v[120:121]
	global_load_dwordx4 v[108:111], v[34:35], off
	global_load_dwordx4 v[112:115], v[32:33], off
.LBB0_379:
	s_and_b32 s3, s3, 1
	s_cmpk_eq_i32 s1, 0x200
	s_cselect_b64 vcc, -1, 0
	v_cndmask_b32_e32 v67, v67, v95, vcc
	v_cndmask_b32_e32 v66, v66, v94, vcc
	v_cndmask_b32_e32 v65, v65, v93, vcc
	v_cndmask_b32_e32 v64, v64, v92, vcc
	v_cndmask_b32_e32 v71, v71, v91, vcc
	v_cndmask_b32_e32 v70, v70, v90, vcc
	v_cndmask_b32_e32 v69, v69, v89, vcc
	v_cndmask_b32_e32 v68, v68, v88, vcc
	s_setprio 1
	s_waitcnt lgkmcnt(0)
	v_mfma_f32_32x32x16_bf16 v[32:47], v[190:193], v[84:87], 0
	v_mfma_f32_32x32x16_bf16 v[48:63], v[214:217], v[84:87], 0
	v_mfma_f32_32x32x16_bf16 v[32:47], v[194:197], v[80:83], v[32:47]
	v_mfma_f32_32x32x16_bf16 v[48:63], v[218:221], v[80:83], v[48:63]
	v_mfma_f32_32x32x16_bf16 v[32:47], v[198:201], v[76:79], v[32:47]
	v_mfma_f32_32x32x16_bf16 v[48:63], v[222:225], v[76:79], v[48:63]
	v_mfma_f32_32x32x16_bf16 v[32:47], v[202:205], v[72:75], v[32:47]
	v_mfma_f32_32x32x16_bf16 v[48:63], v[226:229], v[72:75], v[48:63]
	v_mfma_f32_32x32x16_bf16 v[32:47], v[206:209], v[68:71], v[32:47]
	v_mfma_f32_32x32x16_bf16 v[48:63], v[230:233], v[68:71], v[48:63]
	v_mfma_f32_32x32x16_bf16 v[32:47], v[210:213], v[64:67], v[32:47]
	v_mfma_f32_32x32x16_bf16 v[48:63], v[234:237], v[64:67], v[48:63]
	s_setprio 0
	s_nop 10
	v_max_f32_e32 v121, v48, v48
	v_max_f32_e32 v159, v32, v32
	v_max_f32_e32 v121, v159, v121
	v_max3_f32 v121, v121, v33, v49
	v_max3_f32 v121, v121, v34, v50
	v_max3_f32 v121, v121, v35, v51
	v_max3_f32 v121, v121, v36, v52
	v_max3_f32 v121, v121, v37, v53
	v_max3_f32 v121, v121, v38, v54
	v_max3_f32 v121, v121, v39, v55
	v_max3_f32 v121, v121, v40, v56
	v_max3_f32 v121, v121, v41, v57
	v_max3_f32 v121, v121, v42, v58
	v_max3_f32 v121, v121, v43, v59
	v_max3_f32 v121, v121, v44, v60
	v_max3_f32 v121, v121, v45, v61
	v_max3_f32 v121, v121, v46, v62
	v_cmp_lt_i32_e32 vcc, v177, v176
	v_max3_f32 v159, v121, v47, v63
	s_nop 0
	v_cndmask_b32_e32 v121, v175, v177, vcc
	v_lshlrev_b32_e32 v121, 2, v121
	ds_bpermute_b32 v160, v121, v159
	s_waitcnt lgkmcnt(0)
	v_max_f32_e32 v160, v160, v160
	v_max_f32_e32 v159, v159, v160
	v_add_f32_e32 v160, 0x41000000, v151
	v_cmp_gt_f32_e32 vcc, v159, v160
	s_cbranch_vccz .LBB0_381
	v_max_f32_e32 v159, v159, v159
	v_max_f32_e32 v160, v151, v151
	v_max_f32_e32 v159, v160, v159
	v_sub_f32_e32 v151, v151, v159
	v_exp_f32_e32 v160, v151
	v_mov_b32_e32 v151, v159
	v_pk_mul_f32 v[30:31], v[30:31], v[160:161] op_sel_hi:[1,0]
	v_pk_mul_f32 v[28:29], v[28:29], v[160:161] op_sel_hi:[1,0]
	v_pk_mul_f32 v[26:27], v[26:27], v[160:161] op_sel_hi:[1,0]
	v_pk_mul_f32 v[24:25], v[24:25], v[160:161] op_sel_hi:[1,0]
	v_pk_mul_f32 v[22:23], v[22:23], v[160:161] op_sel_hi:[1,0]
	v_pk_mul_f32 v[20:21], v[20:21], v[160:161] op_sel_hi:[1,0]
	v_pk_mul_f32 v[18:19], v[18:19], v[160:161] op_sel_hi:[1,0]
	v_pk_mul_f32 v[16:17], v[16:17], v[160:161] op_sel_hi:[1,0]
	v_pk_mul_f32 v[14:15], v[14:15], v[160:161] op_sel_hi:[1,0]
	v_pk_mul_f32 v[12:13], v[12:13], v[160:161] op_sel_hi:[1,0]
	v_pk_mul_f32 v[10:11], v[10:11], v[160:161] op_sel_hi:[1,0]
	v_pk_mul_f32 v[8:9], v[8:9], v[160:161] op_sel_hi:[1,0]
	v_pk_mul_f32 v[6:7], v[6:7], v[160:161] op_sel_hi:[1,0]
	v_pk_mul_f32 v[4:5], v[4:5], v[160:161] op_sel_hi:[1,0]
	v_pk_mul_f32 v[2:3], v[2:3], v[160:161] op_sel_hi:[1,0]
	v_pk_mul_f32 v[0:1], v[0:1], v[160:161] op_sel_hi:[1,0]
	v_mul_f32_e32 v119, v119, v160
.LBB0_381:
	s_barrier
	v_sub_f32_e32 v32, v32, v151
	v_exp_f32_e32 v159, v32
	v_sub_f32_e32 v32, v48, v151
	v_sub_f32_e32 v33, v33, v151
	v_exp_f32_e32 v166, v32
	v_exp_f32_e32 v167, v33
	v_sub_f32_e32 v33, v49, v151
	v_exp_f32_e32 v168, v33
	v_add_f32_e32 v32, v159, v166
	v_add_f32_e32 v32, 0, v32
	s_mulk_i32 s3, 0x2400
	v_add_f32_e32 v33, v167, v168
	v_add_f32_e32 v32, v33, v32
	v_sub_f32_e32 v33, v34, v151
	v_exp_f32_e32 v169, v33
	v_sub_f32_e32 v33, v50, v151
	v_exp_f32_e32 v170, v33
	s_add_i32 s1, s1, 64
	s_cmpk_lg_i32 s1, 0x11c0
	v_add_f32_e32 v33, v169, v170
	v_add_f32_e32 v32, v33, v32
	v_sub_f32_e32 v33, v35, v151
	v_exp_f32_e32 v171, v33
	v_sub_f32_e32 v33, v51, v151
	v_exp_f32_e32 v172, v33
	s_nop 0
	v_add_f32_e32 v33, v171, v172
	v_add_f32_e32 v49, v33, v32
	v_sub_f32_e32 v32, v36, v151
	v_exp_f32_e32 v173, v32
	v_sub_f32_e32 v32, v52, v151
	v_exp_f32_e32 v188, v32
	v_sub_f32_e32 v32, v37, v151
	v_exp_f32_e32 v160, v32
	v_sub_f32_e32 v32, v53, v151
	v_exp_f32_e32 v48, v32
	v_add_f32_e32 v161, v173, v188
	v_pk_add_f32 v[32:33], v[160:161], v[48:49]
	s_nop 0
	v_pk_add_f32 v[50:51], v[32:33], v[32:33] op_sel_hi:[0,1]
	v_sub_f32_e32 v32, v38, v151
	v_exp_f32_e32 v49, v32
	v_sub_f32_e32 v32, v54, v151
	v_exp_f32_e32 v161, v32
	v_sub_f32_e32 v32, v39, v151
	v_exp_f32_e32 v162, v32
	v_sub_f32_e32 v32, v55, v151
	v_exp_f32_e32 v50, v32
	v_add_f32_e32 v163, v49, v161
	v_pk_add_f32 v[32:33], v[162:163], v[50:51]
	s_nop 0
	v_pk_add_f32 v[32:33], v[32:33], v[32:33] op_sel_hi:[0,1]
	v_sub_f32_e32 v32, v40, v151
	v_exp_f32_e32 v51, v32
	v_sub_f32_e32 v32, v56, v151
	v_exp_f32_e32 v163, v32
	v_sub_f32_e32 v32, v41, v151
	v_exp_f32_e32 v52, v32
	v_sub_f32_e32 v32, v57, v151
	v_exp_f32_e32 v32, v32
	v_add_f32_e32 v53, v51, v163
	v_pk_add_f32 v[34:35], v[52:53], v[32:33]
	s_nop 0
	v_pk_add_f32 v[34:35], v[34:35], v[34:35] op_sel_hi:[0,1]
	v_sub_f32_e32 v34, v58, v151
	v_sub_f32_e32 v33, v42, v151
	v_exp_f32_e32 v53, v34
	v_sub_f32_e32 v34, v43, v151
	v_exp_f32_e32 v33, v33
	v_exp_f32_e32 v40, v34
	v_sub_f32_e32 v34, v59, v151
	v_exp_f32_e32 v34, v34
	v_add_f32_e32 v41, v33, v53
	v_cvt_pk_bf16_f32 v32, v163, v32
	v_pk_add_f32 v[36:37], v[40:41], v[34:35]
	s_nop 0
	v_pk_add_f32 v[36:37], v[36:37], v[36:37] op_sel_hi:[0,1]
	v_sub_f32_e32 v36, v60, v151
	v_sub_f32_e32 v35, v44, v151
	v_exp_f32_e32 v189, v36
	v_sub_f32_e32 v36, v45, v151
	v_exp_f32_e32 v35, v35
	v_exp_f32_e32 v42, v36
	v_sub_f32_e32 v36, v61, v151
	v_exp_f32_e32 v36, v36
	v_add_f32_e32 v43, v35, v189
	v_pk_add_f32 v[38:39], v[42:43], v[36:37]
	s_nop 0
	v_pk_add_f32 v[38:39], v[38:39], v[38:39] op_sel_hi:[0,1]
	v_sub_f32_e32 v38, v62, v151
	v_sub_f32_e32 v37, v46, v151
	v_exp_f32_e32 v62, v38
	v_sub_f32_e32 v38, v47, v151
	v_exp_f32_e32 v37, v37
	v_exp_f32_e32 v164, v38
	v_sub_f32_e32 v38, v63, v151
	v_exp_f32_e32 v38, v38
	v_add_f32_e32 v165, v37, v62
	v_cvt_pk_bf16_f32 v47, v49, v162
	v_cvt_pk_bf16_f32 v46, v173, v160
	v_pk_add_f32 v[44:45], v[164:165], v[38:39]
	v_add3_u32 v39, v143, s3, v142
	v_add_u32_e32 v49, 0x6800, v39
	ds_read2_b64 v[54:57], v49 offset1:2
	ds_read2_b64 v[58:61], v49 offset0:4 offset1:6
	v_add_f32_e32 v63, v44, v45
	v_cvt_pk_bf16_f32 v44, v159, v167
	v_cvt_pk_bf16_f32 v45, v169, v171
	v_add_u32_e32 v159, 0x7800, v39
	v_add_f32_e32 v119, v119, v63
	s_waitcnt lgkmcnt(1)
	v_mfma_f32_32x32x16_bf16 v[16:31], v[54:57], v[44:47], v[16:31]
	ds_read2_b64 v[54:57], v159 offset0:64 offset1:66
	s_waitcnt lgkmcnt(0)
	v_mfma_f32_32x32x16_bf16 v[0:15], v[54:57], v[44:47], v[0:15]
	v_cvt_pk_bf16_f32 v45, v33, v40
	v_cvt_pk_bf16_f32 v46, v35, v42
	ds_read2_b64 v[40:43], v159 offset0:68 offset1:70
	v_cvt_pk_bf16_f32 v44, v51, v52
	v_cvt_pk_bf16_f32 v47, v37, v164
	v_cvt_pk_bf16_f32 v33, v53, v34
	v_cvt_pk_bf16_f32 v34, v189, v36
	v_mfma_f32_32x32x16_bf16 v[16:31], v[58:61], v[44:47], v[16:31]
	v_cvt_pk_bf16_f32 v35, v62, v38
	ds_read2_b64 v[36:39], v49 offset0:12 offset1:14
	s_waitcnt lgkmcnt(1)
	v_mfma_f32_32x32x16_bf16 v[0:15], v[40:43], v[44:47], v[0:15]
	ds_read2_b64 v[44:47], v49 offset0:8 offset1:10
	v_cvt_pk_bf16_f32 v40, v166, v168
	v_cvt_pk_bf16_f32 v41, v170, v172
	v_cvt_pk_bf16_f32 v42, v188, v48
	v_cvt_pk_bf16_f32 v43, v161, v50
	s_waitcnt lgkmcnt(0)
	s_nop 0
	v_mfma_f32_32x32x16_bf16 v[16:31], v[44:47], v[40:43], v[16:31]
	ds_read2_b64 v[44:47], v159 offset0:72 offset1:74
	v_mfma_f32_32x32x16_bf16 v[16:31], v[36:39], v[32:35], v[16:31]
	ds_read2_b64 v[36:39], v159 offset0:76 offset1:78
	s_waitcnt lgkmcnt(0)
	s_barrier
	v_mfma_f32_32x32x16_bf16 v[0:15], v[44:47], v[40:43], v[0:15]
	v_mfma_f32_32x32x16_bf16 v[0:15], v[36:39], v[32:35], v[0:15]
	s_cbranch_scc0 .LBB0_383
	s_mov_b32 s3, s2
	s_branch .LBB0_377
.LBB0_383:
	v_readfirstlane_b32 s22, v139
	s_bitcmp1_b32 s22, 8
	s_cbranch_scc1 .Lsa_no_e0
	s_barrier
